# baseline (speedup 1.0000x reference)
; #define WAIT_V0() asm volatile("s_waitcnt vmcnt(0)" ::: "memory")
; #define SBAR() __builtin_amdgcn_sched_barrier(0)
; template <int EPI>
; DEVI void gemm_tile(const u16* __restrict__ Ab, long lda, const u16* __restrict__ Bb, long ldb, int K, const EpiArgs& e,
;                     bool have0 = false, const u16* __restrict__ nA = nullptr, const u16* __restrict__ nB = nullptr) {
;     ...
;   for (int t = 0; t < nt; ++t) {
;     const int cur = t & 1;
;     if (t + 1 < nt) GLDS_STAGE(cur ^ 1, t + 1);
;     else if (nA) {
; #pragma unroll
;       for (int i = 0; i < GL; ++i) {
;         __builtin_amdgcn_global_load_lds((const unsigned*)(nA + (long)i * 64 * lda + toffA), (unsigned*)(g_shm + wid * 1024 + i * 8192), 16, 0, 0);
;         __builtin_amdgcn_global_load_lds((const unsigned*)(nB + (long)i * 64 * ldb + toffB), (unsigned*)(g_shm + TILE_B + wid * 1024 + i * 8192), 16, 0, 0);
;       }
;     }
;     const char* sb = g_shm + cur * STAGE_B;
; #pragma unroll
;     for (int ks = 0; ks < 2; ++ks) {
;       bf16x8 Bf[4];
; #pragma unroll
;       for (int n = 0; n < 4; ++n) Bf[n] = *(const bf16x8*)(sb + b_base + n * 2048 + ks * 1024);
; #pragma unroll
;       for (int mh = 0; mh < 2; ++mh) {
;         bf16x8 At[4];
; #pragma unroll
;         for (int m = 0; m < 4; ++m) At[m] = *(const bf16x8*)(sb + a_base + (mh * 4 + m) * 2048 + ks * 1024);
;         __builtin_amdgcn_s_setprio(1);
; #pragma unroll
;         for (int m = 0; m < 4; ++m)
; #pragma unroll
;           for (int n = 0; n < 4; ++n) acc[mh * 4 + m][n] = __builtin_amdgcn_mfma_f32_16x16x32_bf16(Bf[n], At[m], acc[mh * 4 + m][n], 0, 0, 0);
;         __builtin_amdgcn_s_setprio(0);
;       }
;       SBAR();
;     }
;     if (t + 1 < nt) { WAIT_V0(); __syncthreads(); }
;   }
.LBB0_150:
	s_cmp_eq_u32 s101, 0
	s_cbranch_scc0 .Lkl_150_p
	s_setprio 1

; template <int EPI>
; DEVI void gemm_tile(const u16* __restrict__ Ab, long lda, const u16* __restrict__ Bb, long ldb, int K, const EpiArgs& e,
;                     bool have0 = false, const u16* __restrict__ nA = nullptr, const u16* __restrict__ nB = nullptr) {
;     ...
;   for (int t = 0; t < nt; ++t) {
;     const int cur = t & 1;
;     if (t + 1 < nt) GLDS_STAGE(cur ^ 1, t + 1);
;     else if (nA) {
; #pragma unroll
;       for (int i = 0; i < GL; ++i) {
;         __builtin_amdgcn_global_load_lds((const unsigned*)(nA + (long)i * 64 * lda + toffA), (unsigned*)(g_shm + wid * 1024 + i * 8192), 16, 0, 0);
;         __builtin_amdgcn_global_load_lds((const unsigned*)(nB + (long)i * 64 * ldb + toffB), (unsigned*)(g_shm + TILE_B + wid * 1024 + i * 8192), 16, 0, 0);
;       }
;     }
.Lkl_150_s11:
	s_cmp_eq_u32 s100, 1
	s_cbranch_scc0 .Lkl_150
	s_setprio 0
	s_nop 3
	v_readlane_b32 s4, v240, 0
	v_readlane_b32 s5, v240, 1
	v_readlane_b32 s6, v240, 2
	v_readlane_b32 s7, v240, 3
	v_readlane_b32 s8, v240, 4
	v_readlane_b32 s9, v240, 5
	v_readlane_b32 s10, v240, 6
	s_waitcnt lgkmcnt(0)
	s_xor_b32 s3, s3, 0x10000
	v_or_b32_e32 v149, s3, v147
	v_add_u32_e32 v169, v149, v148
	v_add_u32_e32 v149, v149, v146
	s_cmp_eq_u32 s100, 1
	s_cmp_eq_u64 s[10:11], 0
	s_cbranch_scc1 .LBB0_138
	v_readfirstlane_b32 s2, v140
	v_lshl_add_u64 v[132:133], s[10:11], 0, v[130:131]
	s_mov_b32 m0, s2
	v_readfirstlane_b32 s2, v145
	v_lshl_add_u64 v[130:131], s[12:13], 0, v[130:131]
	global_load_lds_dwordx4 v[132:133], off
	s_mov_b32 m0, s2
	s_mov_b64 s[12:13], 0x20000
	v_readfirstlane_b32 s2, v144
	global_load_lds_dwordx4 v[130:131], off
	v_lshl_add_u64 v[134:135], v[132:133], 0, s[12:13]
	s_mov_b32 m0, s2
	v_readfirstlane_b32 s2, v143
	global_load_lds_dwordx4 v[134:135], off
	v_lshl_add_u64 v[134:135], v[130:131], 0, s[12:13]
	s_mov_b32 m0, s2
	v_readfirstlane_b32 s2, v142
	global_load_lds_dwordx4 v[134:135], off
	v_lshl_add_u64 v[134:135], v[132:133], 0, s[96:97]
	s_mov_b32 m0, s2
	v_readfirstlane_b32 s2, v141
	global_load_lds_dwordx4 v[134:135], off
	v_lshl_add_u64 v[134:135], v[130:131], 0, s[96:97]
	s_mov_b32 m0, s2
	s_mov_b64 s[12:13], 0x60000
	v_readfirstlane_b32 s2, v139
	global_load_lds_dwordx4 v[134:135], off
	v_lshl_add_u64 v[132:133], v[132:133], 0, s[12:13]
	s_mov_b32 m0, s2
	v_readfirstlane_b32 s2, v138
	global_load_lds_dwordx4 v[132:133], off
	v_lshl_add_u64 v[130:131], v[130:131], 0, s[12:13]
	s_mov_b32 m0, s2
	s_nop 0
	global_load_lds_dwordx4 v[130:131], off
	s_branch .LBB0_138

; template <int EPI>
; DEVI void gemm_tile(const u16* __restrict__ Ab, long lda, const u16* __restrict__ Bb, long ldb, int K, const EpiArgs& e,
;                     bool have0 = false, const u16* __restrict__ nA = nullptr, const u16* __restrict__ nB = nullptr) {
;     ...
;   for (int t = 0; t < nt; ++t) {
;     const int cur = t & 1;
;     if (t + 1 < nt) GLDS_STAGE(cur ^ 1, t + 1);
;     else if (nA) {
; #pragma unroll
;       for (int i = 0; i < GL; ++i) {
;         __builtin_amdgcn_global_load_lds((const unsigned*)(nA + (long)i * 64 * lda + toffA), (unsigned*)(g_shm + wid * 1024 + i * 8192), 16, 0, 0);
;         __builtin_amdgcn_global_load_lds((const unsigned*)(nB + (long)i * 64 * ldb + toffB), (unsigned*)(g_shm + TILE_B + wid * 1024 + i * 8192), 16, 0, 0);
;       }
;     }
.Lkl_184_s11:
	s_cmp_eq_u32 s100, 1
	s_cbranch_scc0 .Lkl_184
	s_setprio 0
	s_nop 3
	v_readlane_b32 s4, v240, 0
	v_readlane_b32 s5, v240, 1
	v_readlane_b32 s6, v240, 2
	v_readlane_b32 s7, v240, 3
	v_readlane_b32 s8, v240, 4
	v_readlane_b32 s9, v240, 5
	v_readlane_b32 s10, v240, 6
	s_waitcnt lgkmcnt(0)
	s_xor_b32 s22, s22, 0x10000
	v_or_b32_e32 v150, s22, v149
	v_add_u32_e32 v169, v150, v148
	v_or_b32_e32 v150, s22, v146
	v_add_u32_e32 v178, v150, v147
	s_cmp_eq_u32 s100, 1
	s_cmp_eq_u64 s[8:9], 0
	s_cbranch_scc1 .LBB0_172
	v_readfirstlane_b32 s3, v143
	v_lshl_add_u64 v[134:135], s[8:9], 0, v[132:133]
	s_mov_b32 m0, s3
	v_readfirstlane_b32 s3, v145
	v_lshl_add_u64 v[132:133], s[12:13], 0, v[132:133]
	global_load_lds_dwordx4 v[134:135], off
	s_mov_b32 m0, s3
	s_mov_b64 s[12:13], 0x58000
	v_readfirstlane_b32 s3, v144
	global_load_lds_dwordx4 v[132:133], off
	v_lshl_add_u64 v[136:137], v[134:135], 0, s[12:13]
	s_mov_b32 m0, s3
	v_readfirstlane_b32 s3, v142
	global_load_lds_dwordx4 v[136:137], off
	v_lshl_add_u64 v[136:137], v[132:133], 0, s[12:13]
	s_mov_b32 m0, s3
	s_mov_b64 s[12:13], 0xb0000
	v_readfirstlane_b32 s3, v141
	global_load_lds_dwordx4 v[136:137], off
	v_lshl_add_u64 v[136:137], v[134:135], 0, s[12:13]
	s_mov_b32 m0, s3
	v_readfirstlane_b32 s3, v140
	global_load_lds_dwordx4 v[136:137], off
	v_lshl_add_u64 v[136:137], v[132:133], 0, s[12:13]
	s_mov_b32 m0, s3
	s_mov_b64 s[12:13], 0x108000
	v_readfirstlane_b32 s3, v139
	global_load_lds_dwordx4 v[136:137], off
	v_lshl_add_u64 v[134:135], v[134:135], 0, s[12:13]
	s_mov_b32 m0, s3
	v_readfirstlane_b32 s3, v138
	global_load_lds_dwordx4 v[134:135], off
	v_lshl_add_u64 v[132:133], v[132:133], 0, s[12:13]
	s_mov_b32 m0, s3
	s_nop 0
	global_load_lds_dwordx4 v[132:133], off
	s_branch .LBB0_172

; template <int EPI>
; DEVI void gemm_tile(const u16* __restrict__ Ab, long lda, const u16* __restrict__ Bb, long ldb, int K, const EpiArgs& e,
;                     bool have0 = false, const u16* __restrict__ nA = nullptr, const u16* __restrict__ nB = nullptr) {
;     ...
;   for (int t = 0; t < nt; ++t) {
;     const int cur = t & 1;
;     if (t + 1 < nt) GLDS_STAGE(cur ^ 1, t + 1);
;     else if (nA) {
; #pragma unroll
;       for (int i = 0; i < GL; ++i) {
;         __builtin_amdgcn_global_load_lds((const unsigned*)(nA + (long)i * 64 * lda + toffA), (unsigned*)(g_shm + wid * 1024 + i * 8192), 16, 0, 0);
;         __builtin_amdgcn_global_load_lds((const unsigned*)(nB + (long)i * 64 * ldb + toffB), (unsigned*)(g_shm + TILE_B + wid * 1024 + i * 8192), 16, 0, 0);
;       }
;     }
.Lkl_359_s11:
	s_cmp_eq_u32 s100, 1
	s_cbranch_scc0 .Lkl_359
	s_setprio 0
	s_nop 3
	v_readlane_b32 s4, v240, 0
	v_readlane_b32 s5, v240, 1
	v_readlane_b32 s6, v240, 2
	v_readlane_b32 s7, v240, 3
	v_readlane_b32 s8, v240, 4
	v_readlane_b32 s9, v240, 5
	v_readlane_b32 s10, v240, 6
	s_waitcnt lgkmcnt(0)
	s_xor_b32 s3, s3, 0x10000
	v_or_b32_e32 v150, s3, v149
	v_add_u32_e32 v169, v150, v148
	v_or_b32_e32 v150, s3, v146
	v_add_u32_e32 v178, v150, v147
	s_cmp_eq_u32 s100, 1
	s_cmp_eq_u64 s[8:9], 0
	s_cbranch_scc1 .LBB0_362
	v_readfirstlane_b32 s2, v142
	v_lshl_add_u64 v[132:133], s[8:9], 0, v[130:131]
	s_mov_b32 m0, s2
	v_readfirstlane_b32 s2, v145
	v_lshl_add_u64 v[130:131], s[12:13], 0, v[130:131]
	global_load_lds_dwordx4 v[132:133], off
	s_mov_b32 m0, s2
	v_readfirstlane_b32 s2, v144
	global_load_lds_dwordx4 v[130:131], off
	v_lshl_add_u64 v[134:135], v[132:133], 0, s[96:97]
	s_mov_b32 m0, s2
	v_readfirstlane_b32 s2, v143
	global_load_lds_dwordx4 v[134:135], off
	v_lshl_add_u64 v[134:135], v[130:131], 0, s[96:97]
	s_mov_b32 m0, s2
	s_mov_b64 s[12:13], 0x80000
	v_readfirstlane_b32 s2, v141
	global_load_lds_dwordx4 v[134:135], off
	v_lshl_add_u64 v[134:135], v[132:133], 0, s[12:13]
	s_mov_b32 m0, s2
	v_readfirstlane_b32 s2, v140
	global_load_lds_dwordx4 v[134:135], off
	v_lshl_add_u64 v[134:135], v[130:131], 0, s[12:13]
	s_mov_b32 m0, s2
	s_mov_b64 s[12:13], 0xc0000
	v_readfirstlane_b32 s2, v139
	global_load_lds_dwordx4 v[134:135], off
	v_lshl_add_u64 v[132:133], v[132:133], 0, s[12:13]
	s_mov_b32 m0, s2
	v_readfirstlane_b32 s2, v138
	global_load_lds_dwordx4 v[132:133], off
	v_lshl_add_u64 v[130:131], v[130:131], 0, s[12:13]
	s_mov_b32 m0, s2
	s_nop 0
	global_load_lds_dwordx4 v[130:131], off

; template <int EPI>
; DEVI void gemm_tile(const u16* __restrict__ Ab, long lda, const u16* __restrict__ Bb, long ldb, int K, const EpiArgs& e,
;                     bool have0 = false, const u16* __restrict__ nA = nullptr, const u16* __restrict__ nB = nullptr) {
;     ...
;   for (int t = 0; t < nt; ++t) {
;     const int cur = t & 1;
;     if (t + 1 < nt) GLDS_STAGE(cur ^ 1, t + 1);
;     else if (nA) {
; #pragma unroll
;       for (int i = 0; i < GL; ++i) {
;         __builtin_amdgcn_global_load_lds((const unsigned*)(nA + (long)i * 64 * lda + toffA), (unsigned*)(g_shm + wid * 1024 + i * 8192), 16, 0, 0);
;         __builtin_amdgcn_global_load_lds((const unsigned*)(nB + (long)i * 64 * ldb + toffB), (unsigned*)(g_shm + TILE_B + wid * 1024 + i * 8192), 16, 0, 0);
;       }
;     }
.Lkl_459_s11:
	s_cmp_eq_u32 s100, 1
	s_cbranch_scc0 .Lkl_459
	s_setprio 0
	s_nop 3
	v_readlane_b32 s4, v240, 0
	v_readlane_b32 s5, v240, 1
	v_readlane_b32 s6, v240, 2
	v_readlane_b32 s7, v240, 3
	v_readlane_b32 s8, v240, 4
	v_readlane_b32 s9, v240, 5
	v_readlane_b32 s10, v240, 6
	s_waitcnt lgkmcnt(0)
	s_xor_b32 s3, s3, 0x10000
	v_or_b32_e32 v150, s3, v149
	v_add_u32_e32 v169, v150, v148
	v_or_b32_e32 v150, s3, v146
	v_add_u32_e32 v178, v150, v147
	s_cmp_eq_u32 s100, 1
	s_cmp_eq_u64 s[8:9], 0
	s_cbranch_scc1 .LBB0_447
	v_readfirstlane_b32 s2, v142
	v_lshl_add_u64 v[132:133], s[8:9], 0, v[130:131]
	s_mov_b32 m0, s2
	v_readfirstlane_b32 s2, v145
	v_lshl_add_u64 v[130:131], s[12:13], 0, v[130:131]
	global_load_lds_dwordx4 v[132:133], off
	s_mov_b32 m0, s2
	s_mov_b64 s[12:13], 0x20000
	v_readfirstlane_b32 s2, v144
	global_load_lds_dwordx4 v[130:131], off
	v_lshl_add_u64 v[134:135], v[132:133], 0, s[12:13]
	s_mov_b32 m0, s2
	v_readfirstlane_b32 s2, v143
	global_load_lds_dwordx4 v[134:135], off
	v_lshl_add_u64 v[134:135], v[130:131], 0, s[12:13]
	s_mov_b32 m0, s2
	v_readfirstlane_b32 s2, v141
	global_load_lds_dwordx4 v[134:135], off
	v_lshl_add_u64 v[134:135], v[132:133], 0, s[96:97]
	s_mov_b32 m0, s2
	v_readfirstlane_b32 s2, v140
	global_load_lds_dwordx4 v[134:135], off
	v_lshl_add_u64 v[134:135], v[130:131], 0, s[96:97]
	s_mov_b32 m0, s2
	s_mov_b64 s[12:13], 0x60000
	v_readfirstlane_b32 s2, v139
	global_load_lds_dwordx4 v[134:135], off
	v_lshl_add_u64 v[132:133], v[132:133], 0, s[12:13]
	s_mov_b32 m0, s2
	v_readfirstlane_b32 s2, v138
	global_load_lds_dwordx4 v[132:133], off
	v_lshl_add_u64 v[130:131], v[130:131], 0, s[12:13]
	s_mov_b32 m0, s2
	s_nop 0
	global_load_lds_dwordx4 v[130:131], off
	s_branch .LBB0_447

; template <int EPI>
; DEVI void gemm_tile(const u16* __restrict__ Ab, long lda, const u16* __restrict__ Bb, long ldb, int K, const EpiArgs& e,
;                     bool have0 = false, const u16* __restrict__ nA = nullptr, const u16* __restrict__ nB = nullptr) {
;     ...
;   for (int t = 0; t < nt; ++t) {
;     const int cur = t & 1;
;     if (t + 1 < nt) GLDS_STAGE(cur ^ 1, t + 1);
;     else if (nA) {
; #pragma unroll
;       for (int i = 0; i < GL; ++i) {
;         __builtin_amdgcn_global_load_lds((const unsigned*)(nA + (long)i * 64 * lda + toffA), (unsigned*)(g_shm + wid * 1024 + i * 8192), 16, 0, 0);
;         __builtin_amdgcn_global_load_lds((const unsigned*)(nB + (long)i * 64 * ldb + toffB), (unsigned*)(g_shm + TILE_B + wid * 1024 + i * 8192), 16, 0, 0);
;       }
;     }
.Lkl_710_s11:
	s_cmp_eq_u32 s100, 1
	s_cbranch_scc0 .Lkl_710
	s_setprio 0
	s_nop 3
	v_readlane_b32 s4, v240, 0
	v_readlane_b32 s5, v240, 1
	v_readlane_b32 s6, v240, 2
	v_readlane_b32 s7, v240, 3
	v_readlane_b32 s8, v240, 4
	v_readlane_b32 s9, v240, 5
	v_readlane_b32 s10, v240, 6
	s_waitcnt lgkmcnt(0)
	s_xor_b32 s3, s3, 0x10000
	v_or_b32_e32 v150, s3, v149
	v_add_u32_e32 v169, v150, v148
	v_or_b32_e32 v150, s3, v146
	v_add_u32_e32 v178, v150, v147
	s_cmp_eq_u32 s100, 1
	s_cmp_eq_u64 s[8:9], 0
	s_cbranch_scc1 .LBB0_698
	v_readfirstlane_b32 s2, v142
	v_lshl_add_u64 v[132:133], s[8:9], 0, v[130:131]
	s_mov_b32 m0, s2
	v_readfirstlane_b32 s2, v145
	v_lshl_add_u64 v[130:131], s[10:11], 0, v[130:131]
	global_load_lds_dwordx4 v[132:133], off
	s_mov_b32 m0, s2
	s_mov_b64 s[10:11], 0x20000
	v_readfirstlane_b32 s2, v144
	global_load_lds_dwordx4 v[130:131], off
	v_lshl_add_u64 v[134:135], v[132:133], 0, s[10:11]
	s_mov_b32 m0, s2
	v_readfirstlane_b32 s2, v143
	global_load_lds_dwordx4 v[134:135], off
	v_lshl_add_u64 v[134:135], v[130:131], 0, s[10:11]
	s_mov_b32 m0, s2
	v_readfirstlane_b32 s2, v141
	global_load_lds_dwordx4 v[134:135], off
	v_lshl_add_u64 v[134:135], v[132:133], 0, s[96:97]
	s_mov_b32 m0, s2
	v_readfirstlane_b32 s2, v140
	global_load_lds_dwordx4 v[134:135], off
	v_lshl_add_u64 v[134:135], v[130:131], 0, s[96:97]
	s_mov_b32 m0, s2
	s_mov_b64 s[10:11], 0x60000
	v_readfirstlane_b32 s2, v139
	global_load_lds_dwordx4 v[134:135], off
	v_lshl_add_u64 v[132:133], v[132:133], 0, s[10:11]
	s_mov_b32 m0, s2
	v_readfirstlane_b32 s2, v138
	global_load_lds_dwordx4 v[132:133], off
	v_lshl_add_u64 v[130:131], v[130:131], 0, s[10:11]
	s_mov_b32 m0, s2
	s_nop 0
	global_load_lds_dwordx4 v[130:131], off
	s_branch .LBB0_698

; template <int EPI>
; DEVI void gemm_tile(const u16* __restrict__ Ab, long lda, const u16* __restrict__ Bb, long ldb, int K, const EpiArgs& e,
;                     bool have0 = false, const u16* __restrict__ nA = nullptr, const u16* __restrict__ nB = nullptr) {
;     ...
;   for (int t = 0; t < nt; ++t) {
;     const int cur = t & 1;
;     if (t + 1 < nt) GLDS_STAGE(cur ^ 1, t + 1);
;     else if (nA) {
; #pragma unroll
;       for (int i = 0; i < GL; ++i) {
;         __builtin_amdgcn_global_load_lds((const unsigned*)(nA + (long)i * 64 * lda + toffA), (unsigned*)(g_shm + wid * 1024 + i * 8192), 16, 0, 0);
;         __builtin_amdgcn_global_load_lds((const unsigned*)(nB + (long)i * 64 * ldb + toffB), (unsigned*)(g_shm + TILE_B + wid * 1024 + i * 8192), 16, 0, 0);
;       }
;     }
.Lkl_1085_s11:
	s_cmp_eq_u32 s100, 1
	s_cbranch_scc0 .Lkl_1085
	s_setprio 0
	s_nop 3
	v_readlane_b32 s4, v240, 0
	v_readlane_b32 s5, v240, 1
	v_readlane_b32 s6, v240, 2
	v_readlane_b32 s7, v240, 3
	v_readlane_b32 s8, v240, 4
	v_readlane_b32 s9, v240, 5
	v_readlane_b32 s10, v240, 6
	s_waitcnt lgkmcnt(0)
	s_xor_b32 s3, s3, 0x10000
	v_or_b32_e32 v150, s3, v149
	v_add_u32_e32 v169, v150, v148
	v_or_b32_e32 v150, s3, v146
	v_add_u32_e32 v178, v150, v147
	s_cmp_eq_u32 s100, 1
	s_cmp_eq_u64 s[8:9], 0
	s_cbranch_scc1 .LBB0_1073
	v_readfirstlane_b32 s2, v142
	v_lshl_add_u64 v[134:135], s[8:9], 0, v[132:133]
	s_mov_b32 m0, s2
	v_readfirstlane_b32 s2, v145
	v_lshl_add_u64 v[132:133], s[12:13], 0, v[132:133]
	global_load_lds_dwordx4 v[134:135], off
	s_mov_b32 m0, s2
	s_mov_b64 s[12:13], 0x20000
	v_readfirstlane_b32 s2, v144
	global_load_lds_dwordx4 v[132:133], off
	v_lshl_add_u64 v[136:137], v[134:135], 0, s[12:13]
	s_mov_b32 m0, s2
	v_readfirstlane_b32 s2, v143
	global_load_lds_dwordx4 v[136:137], off
	v_lshl_add_u64 v[136:137], v[132:133], 0, s[12:13]
	s_mov_b32 m0, s2
	v_readfirstlane_b32 s2, v141
	global_load_lds_dwordx4 v[136:137], off
	v_lshl_add_u64 v[136:137], v[134:135], 0, s[96:97]
	s_mov_b32 m0, s2
	v_readfirstlane_b32 s2, v140
	global_load_lds_dwordx4 v[136:137], off
	v_lshl_add_u64 v[136:137], v[132:133], 0, s[96:97]
	s_mov_b32 m0, s2
	s_mov_b64 s[12:13], 0x60000
	v_readfirstlane_b32 s2, v139
	global_load_lds_dwordx4 v[136:137], off
	v_lshl_add_u64 v[134:135], v[134:135], 0, s[12:13]
	s_mov_b32 m0, s2
	v_readfirstlane_b32 s2, v138
	global_load_lds_dwordx4 v[134:135], off
	v_lshl_add_u64 v[132:133], v[132:133], 0, s[12:13]
	s_mov_b32 m0, s2
	s_nop 0
	global_load_lds_dwordx4 v[132:133], off
	s_branch .LBB0_1073

; template <int EPI>
; DEVI void gemm_tile(const u16* __restrict__ Ab, long lda, const u16* __restrict__ Bb, long ldb, int K, const EpiArgs& e,
;                     bool have0 = false, const u16* __restrict__ nA = nullptr, const u16* __restrict__ nB = nullptr) {
;     ...
;   for (int t = 0; t < nt; ++t) {
;     const int cur = t & 1;
;     if (t + 1 < nt) GLDS_STAGE(cur ^ 1, t + 1);
;     else if (nA) {
; #pragma unroll
;       for (int i = 0; i < GL; ++i) {
;         __builtin_amdgcn_global_load_lds((const unsigned*)(nA + (long)i * 64 * lda + toffA), (unsigned*)(g_shm + wid * 1024 + i * 8192), 16, 0, 0);
;         __builtin_amdgcn_global_load_lds((const unsigned*)(nB + (long)i * 64 * ldb + toffB), (unsigned*)(g_shm + TILE_B + wid * 1024 + i * 8192), 16, 0, 0);
;       }
;     }
.Lkl_1370_s11:
	s_cmp_eq_u32 s100, 1
	s_cbranch_scc0 .Lkl_1370
	s_setprio 0
	s_nop 3
	v_readlane_b32 s4, v240, 0
	v_readlane_b32 s5, v240, 1
	v_readlane_b32 s6, v240, 2
	v_readlane_b32 s7, v240, 3
	v_readlane_b32 s8, v240, 4
	v_readlane_b32 s9, v240, 5
	v_readlane_b32 s10, v240, 6
	s_waitcnt lgkmcnt(0)
	s_xor_b32 s3, s3, 0x10000
	v_or_b32_e32 v149, s3, v147
	v_add_u32_e32 v169, v149, v148
	v_add_u32_e32 v149, v149, v146
	s_cmp_eq_u32 s100, 1
	s_cmp_eq_u64 s[10:11], 0
	s_cbranch_scc1 .LBB0_1358
	v_readfirstlane_b32 s2, v140
	v_lshl_add_u64 v[132:133], s[10:11], 0, v[130:131]
	s_mov_b32 m0, s2
	v_readfirstlane_b32 s2, v145
	v_lshl_add_u64 v[130:131], s[16:17], 0, v[130:131]
	global_load_lds_dwordx4 v[132:133], off
	s_mov_b32 m0, s2
	s_mov_b64 s[16:17], 0x20000
	v_readfirstlane_b32 s2, v144
	global_load_lds_dwordx4 v[130:131], off
	v_lshl_add_u64 v[134:135], v[132:133], 0, s[16:17]
	s_mov_b32 m0, s2
	v_readfirstlane_b32 s2, v143
	global_load_lds_dwordx4 v[134:135], off
	v_lshl_add_u64 v[134:135], v[130:131], 0, s[16:17]
	s_mov_b32 m0, s2
	v_readfirstlane_b32 s2, v142
	global_load_lds_dwordx4 v[134:135], off
	v_lshl_add_u64 v[134:135], v[132:133], 0, s[96:97]
	s_mov_b32 m0, s2
	v_readfirstlane_b32 s2, v141
	global_load_lds_dwordx4 v[134:135], off
	v_lshl_add_u64 v[134:135], v[130:131], 0, s[96:97]
	s_mov_b32 m0, s2
	s_mov_b64 s[16:17], 0x60000
	v_readfirstlane_b32 s2, v139
	global_load_lds_dwordx4 v[134:135], off
	v_lshl_add_u64 v[132:133], v[132:133], 0, s[16:17]
	s_mov_b32 m0, s2
	v_readfirstlane_b32 s2, v138
	global_load_lds_dwordx4 v[132:133], off
	v_lshl_add_u64 v[130:131], v[130:131], 0, s[16:17]
	s_mov_b32 m0, s2
	s_nop 0
	global_load_lds_dwordx4 v[130:131], off
	s_branch .LBB0_1358

; template <int EPI>
; DEVI void gemm_tile(const u16* __restrict__ Ab, long lda, const u16* __restrict__ Bb, long ldb, int K, const EpiArgs& e,
;                     bool have0 = false, const u16* __restrict__ nA = nullptr, const u16* __restrict__ nB = nullptr) {
;     ...
;   for (int t = 0; t < nt; ++t) {
;     const int cur = t & 1;
;     if (t + 1 < nt) GLDS_STAGE(cur ^ 1, t + 1);
;     else if (nA) {
; #pragma unroll
;       for (int i = 0; i < GL; ++i) {
;         __builtin_amdgcn_global_load_lds((const unsigned*)(nA + (long)i * 64 * lda + toffA), (unsigned*)(g_shm + wid * 1024 + i * 8192), 16, 0, 0);
;         __builtin_amdgcn_global_load_lds((const unsigned*)(nB + (long)i * 64 * ldb + toffB), (unsigned*)(g_shm + TILE_B + wid * 1024 + i * 8192), 16, 0, 0);
;       }
;     }
.Lkl_1404_s11:
	s_cmp_eq_u32 s100, 1
	s_cbranch_scc0 .Lkl_1404
	s_setprio 0
	s_nop 3
	v_readlane_b32 s4, v240, 0
	v_readlane_b32 s5, v240, 1
	v_readlane_b32 s6, v240, 2
	v_readlane_b32 s7, v240, 3
	v_readlane_b32 s8, v240, 4
	v_readlane_b32 s9, v240, 5
	v_readlane_b32 s10, v240, 6
	s_waitcnt lgkmcnt(0)
	s_xor_b32 s26, s26, 0x10000
	v_or_b32_e32 v150, s26, v149
	v_add_u32_e32 v169, v150, v148
	v_or_b32_e32 v150, s26, v146
	v_add_u32_e32 v178, v150, v147
	s_cmp_eq_u32 s100, 1
	s_cmp_eq_u64 s[10:11], 0
	s_cbranch_scc1 .LBB0_1392
	v_readfirstlane_b32 s3, v143
	v_lshl_add_u64 v[134:135], s[10:11], 0, v[132:133]
	s_mov_b32 m0, s3
	v_readfirstlane_b32 s3, v145
	v_lshl_add_u64 v[132:133], s[16:17], 0, v[132:133]
	global_load_lds_dwordx4 v[134:135], off
	s_mov_b32 m0, s3
	s_mov_b64 s[16:17], 0x58000
	v_readfirstlane_b32 s3, v144
	global_load_lds_dwordx4 v[132:133], off
	v_lshl_add_u64 v[136:137], v[134:135], 0, s[16:17]
	s_mov_b32 m0, s3
	v_readfirstlane_b32 s3, v142
	global_load_lds_dwordx4 v[136:137], off
	v_lshl_add_u64 v[136:137], v[132:133], 0, s[16:17]
	s_mov_b32 m0, s3
	s_mov_b64 s[16:17], 0xb0000
	v_readfirstlane_b32 s3, v141
	global_load_lds_dwordx4 v[136:137], off
	v_lshl_add_u64 v[136:137], v[134:135], 0, s[16:17]
	s_mov_b32 m0, s3
	v_readfirstlane_b32 s3, v140
	global_load_lds_dwordx4 v[136:137], off
	v_lshl_add_u64 v[136:137], v[132:133], 0, s[16:17]
	s_mov_b32 m0, s3
	s_mov_b64 s[16:17], 0x108000
	v_readfirstlane_b32 s3, v139
	global_load_lds_dwordx4 v[136:137], off
	v_lshl_add_u64 v[134:135], v[134:135], 0, s[16:17]
	s_mov_b32 m0, s3
	v_readfirstlane_b32 s3, v138
	global_load_lds_dwordx4 v[134:135], off
	v_lshl_add_u64 v[132:133], v[132:133], 0, s[16:17]
	s_mov_b32 m0, s3
	s_nop 0
	global_load_lds_dwordx4 v[132:133], off
	s_branch .LBB0_1392
